# step25: outproj0 walks each XCD list's m-tiles in reverse token order (most recently written scan output first) for last-level-cache locality, on top of step20
# baseline (speedup 1.0000x reference)
.LBB0_611:
	s_or_b64 exec, exec, s[34:35]
	s_xor_b32 s6, s50, 60
	s_lshl_b32 s6, s6, 6
	s_add_i32 s6, s6, s45
	s_and_b32 s34, s6, 0xffffff00
	v_or_b32_e32 v2, s34, v144
	s_lshl_b32 s6, s50, 8
	v_ashrrev_i32_e32 v3, 31, v2
	s_and_b32 s35, s6, 0x300
	v_lshlrev_b64 v[2:3], 12, v[2:3]
	v_readfirstlane_b32 s6, v145
	v_lshl_add_u64 v[136:137], v[132:133], 0, v[2:3]
	v_or_b32_e32 v2, s35, v144
	s_mov_b32 m0, s6
	v_readfirstlane_b32 s6, v156
	v_lshlrev_b32_e32 v130, 12, v2
	s_barrier
	global_load_lds_dwordx4 v[136:137], off
	v_lshl_add_u64 v[140:141], v[136:137], 0, s[16:17]
	s_mov_b32 m0, s6
	v_readfirstlane_b32 s6, v157
	v_lshl_add_u64 v[138:139], v[134:135], 0, v[130:131]
	global_load_lds_dwordx4 v[140:141], off
	s_mov_b32 m0, s6
	v_readfirstlane_b32 s6, v158
	global_load_lds_dwordx4 v[138:139], off
	v_lshl_add_u64 v[142:143], v[138:139], 0, s[16:17]
	s_mov_b32 m0, s6
	v_readfirstlane_b32 s6, v159
	global_load_lds_dwordx4 v[142:143], off
	v_lshl_add_u64 v[2:3], v[136:137], 0, 64
	s_mov_b32 m0, s6
	v_readfirstlane_b32 s6, v160
	global_load_lds_dwordx4 v[2:3], off
	v_lshl_add_u64 v[2:3], v[136:137], 0, s[18:19]
	s_mov_b32 m0, s6
	v_readfirstlane_b32 s6, v161
	global_load_lds_dwordx4 v[2:3], off
	v_lshl_add_u64 v[2:3], v[138:139], 0, 64
	s_mov_b32 m0, s6
	v_readfirstlane_b32 s6, v162
	global_load_lds_dwordx4 v[2:3], off
	v_lshl_add_u64 v[2:3], v[138:139], 0, s[18:19]
	s_mov_b32 m0, s6
	v_readfirstlane_b32 s6, v147
	global_load_lds_dwordx4 v[2:3], off
	v_lshl_add_u64 v[2:3], v[136:137], 0, s[20:21]
	s_mov_b32 m0, s6
	v_readfirstlane_b32 s6, v148
	global_load_lds_dwordx4 v[2:3], off
	v_lshl_add_u64 v[2:3], v[136:137], 0, s[22:23]
	s_mov_b32 m0, s6
	v_readfirstlane_b32 s6, v149
	global_load_lds_dwordx4 v[2:3], off
	v_lshl_add_u64 v[2:3], v[138:139], 0, s[20:21]
	s_mov_b32 m0, s6
	v_readfirstlane_b32 s6, v150
	global_load_lds_dwordx4 v[2:3], off
	v_lshl_add_u64 v[2:3], v[138:139], 0, s[22:23]
	s_mov_b32 m0, s6
	s_mov_b32 s37, 3
	global_load_lds_dwordx4 v[2:3], off
	v_mov_b32_e32 v2, 0
	s_mov_b32 s38, 0
	s_mov_b32 s36, 0
	v_mov_b32_e32 v3, v2
	v_mov_b32_e32 v4, v2
	v_mov_b32_e32 v5, v2
	v_mov_b32_e32 v6, v2
	v_mov_b32_e32 v7, v2
	v_mov_b32_e32 v8, v2
	v_mov_b32_e32 v9, v2
	v_mov_b32_e32 v10, v2
	v_mov_b32_e32 v11, v2
	v_mov_b32_e32 v12, v2
	v_mov_b32_e32 v13, v2
	v_mov_b32_e32 v14, v2
	v_mov_b32_e32 v15, v2
	v_mov_b32_e32 v16, v2
	v_mov_b32_e32 v17, v2
	v_mov_b32_e32 v18, v2
	v_mov_b32_e32 v19, v2
	v_mov_b32_e32 v20, v2
	v_mov_b32_e32 v21, v2
	v_mov_b32_e32 v22, v2
	v_mov_b32_e32 v23, v2
	v_mov_b32_e32 v24, v2
	v_mov_b32_e32 v25, v2
	v_mov_b32_e32 v26, v2
	v_mov_b32_e32 v27, v2
	v_mov_b32_e32 v28, v2
	v_mov_b32_e32 v29, v2
	v_mov_b32_e32 v30, v2
	v_mov_b32_e32 v31, v2
	v_mov_b32_e32 v32, v2
	v_mov_b32_e32 v33, v2
	v_mov_b32_e32 v34, v2
	v_mov_b32_e32 v35, v2
	v_mov_b32_e32 v36, v2
	v_mov_b32_e32 v37, v2
	v_mov_b32_e32 v38, v2
	v_mov_b32_e32 v39, v2
	v_mov_b32_e32 v40, v2
	v_mov_b32_e32 v41, v2
	v_mov_b32_e32 v42, v2
	v_mov_b32_e32 v43, v2
	v_mov_b32_e32 v44, v2
	v_mov_b32_e32 v45, v2
	v_mov_b32_e32 v46, v2
	v_mov_b32_e32 v47, v2
	v_mov_b32_e32 v48, v2
	v_mov_b32_e32 v49, v2
	v_mov_b32_e32 v50, v2
	v_mov_b32_e32 v51, v2
	v_mov_b32_e32 v52, v2
	v_mov_b32_e32 v53, v2
	v_mov_b32_e32 v54, v2
	v_mov_b32_e32 v55, v2
	v_mov_b32_e32 v56, v2
	v_mov_b32_e32 v57, v2
	v_mov_b32_e32 v58, v2
	v_mov_b32_e32 v59, v2
	v_mov_b32_e32 v60, v2
	v_mov_b32_e32 v61, v2
	v_mov_b32_e32 v62, v2
	v_mov_b32_e32 v63, v2
	v_mov_b32_e32 v64, v2
	v_mov_b32_e32 v65, v2
	v_mov_b32_e32 v66, v2
	v_mov_b32_e32 v67, v2
	v_mov_b32_e32 v68, v2
	v_mov_b32_e32 v69, v2
	v_mov_b32_e32 v70, v2
	v_mov_b32_e32 v71, v2
	v_mov_b32_e32 v72, v2
	v_mov_b32_e32 v73, v2
	v_mov_b32_e32 v74, v2
	v_mov_b32_e32 v75, v2
	v_mov_b32_e32 v76, v2
	v_mov_b32_e32 v77, v2
	v_mov_b32_e32 v78, v2
	v_mov_b32_e32 v79, v2
	v_mov_b32_e32 v80, v2
	v_mov_b32_e32 v81, v2
	v_mov_b32_e32 v82, v2
	v_mov_b32_e32 v83, v2
	v_mov_b32_e32 v84, v2
	v_mov_b32_e32 v85, v2
	v_mov_b32_e32 v86, v2
	v_mov_b32_e32 v87, v2
	v_mov_b32_e32 v88, v2
	v_mov_b32_e32 v89, v2
	v_mov_b32_e32 v90, v2
	v_mov_b32_e32 v91, v2
	v_mov_b32_e32 v92, v2
	v_mov_b32_e32 v93, v2
	v_mov_b32_e32 v94, v2
	v_mov_b32_e32 v95, v2
	v_mov_b32_e32 v96, v2
	v_mov_b32_e32 v97, v2
	v_mov_b32_e32 v98, v2
	v_mov_b32_e32 v99, v2
	v_mov_b32_e32 v100, v2
	v_mov_b32_e32 v101, v2
	v_mov_b32_e32 v102, v2
	v_mov_b32_e32 v103, v2
	v_mov_b32_e32 v104, v2
	v_mov_b32_e32 v105, v2
	v_mov_b32_e32 v106, v2
	v_mov_b32_e32 v107, v2
	v_mov_b32_e32 v108, v2
	v_mov_b32_e32 v109, v2
	v_mov_b32_e32 v110, v2
	v_mov_b32_e32 v111, v2
	v_mov_b32_e32 v112, v2
	v_mov_b32_e32 v113, v2
	v_mov_b32_e32 v114, v2
	v_mov_b32_e32 v115, v2
	v_mov_b32_e32 v116, v2
	v_mov_b32_e32 v117, v2
	v_mov_b32_e32 v118, v2
	v_mov_b32_e32 v119, v2
	v_mov_b32_e32 v120, v2
	v_mov_b32_e32 v121, v2
	v_mov_b32_e32 v122, v2
	v_mov_b32_e32 v123, v2
	v_mov_b32_e32 v124, v2
	v_mov_b32_e32 v125, v2
	v_mov_b32_e32 v126, v2
	v_mov_b32_e32 v127, v2
	v_mov_b32_e32 v128, v2
	v_mov_b32_e32 v129, v2
